# HGRN item: LDS-protecting barrier moved behind the gate prologue; the prologue's 16 ds_write2 are collected after it (values parked in dead registers)
# baseline (speedup 1.0000x reference)
.LBB0_231:
	s_and_b64 vcc, exec, s[2:3]
	s_cbranch_vccz .LBB0_291
	v_mov_b32_e32 v0, v206
	s_addk_i32 s6, 0xfe00
	v_ashrrev_i32_e32 v0, 8, v0
	v_mov_b32_e32 v28, v206
	v_mov_b32_e32 v22, v206
	v_mov_b32_e32 v1, v206
	v_add_u32_e32 v16, s6, v0
	s_movk_i32 s2, 0x100
	v_bfe_u32 v17, v22, 6, 2
	v_ashrrev_i32_e32 v0, 9, v16
	v_cmp_gt_u32_e32 vcc, s2, v1
	v_xor_b32_e32 v1, 3, v17
	v_and_b32_e32 v26, 15, v22
	v_cndmask_b32_e32 v27, v1, v17, vcc
	v_ashrrev_i32_e32 v1, 31, v0
	v_lshlrev_b64 v[24:25], 13, v[0:1]
	v_lshlrev_b32_e32 v0, 6, v16
	s_movk_i32 s2, 0x1fc0
	v_lshlrev_b32_e32 v32, 4, v27
	v_and_or_b32 v20, v0, s2, v24
	v_or_b32_e32 v19, v32, v26
	v_or_b32_e32 v24, v20, v19
	v_mov_b64_e32 v[0:1], s[68:69]
	v_lshrrev_b32_e32 v2, 1, v16
	v_mad_u64_u32 v[0:1], s[2:3], v24, s13, v[0:1]
	v_and_b32_e32 v34, 0xc0, v2
	v_bfe_u32 v23, v22, 4, 2
	v_mad_i32_i24 v1, v25, s13, v1
	v_lshlrev_b32_e32 v176, 1, v34
	v_lshl_add_u64 v[0:1], v[0:1], 0, v[176:177]
	v_lshlrev_b32_e32 v2, 4, v23
	v_mov_b32_e32 v3, v177
	v_lshl_add_u64 v[0:1], v[0:1], 0, v[2:3]
	s_mov_b64 s[2:3], 0x3e80a00
	v_lshl_add_u64 v[2:3], v[0:1], 0, s[2:3]
	s_mov_b32 s2, 0x3e80000
	v_add_co_u32_e32 v0, vcc, s2, v0
	v_mov_b32_e32 v33, v206
	s_nop 0
	v_addc_co_u32_e32 v1, vcc, 0, v1, vcc
	global_load_dwordx4 v[4:7], v[0:1], off offset:2560
	s_nop 0
	global_load_dwordx4 v[0:3], v[2:3], off offset:64
	v_mov_b64_e32 v[36:37], s[76:77]
	v_bfe_u32 v29, v33, 6, 2
	v_bfe_u32 v30, v33, 2, 6
	v_lshlrev_b32_e32 v8, 4, v33
	v_lshlrev_b32_e32 v18, 4, v29
	v_and_b32_e32 v31, 48, v8
	v_or_b32_e32 v8, v20, v30
	v_or_b32_e32 v20, v20, v18
	v_and_b32_e32 v21, 63, v33
	v_mad_u64_u32 v[8:9], s[2:3], v8, s13, v[36:37]
	v_mad_u64_u32 v[36:37], s[2:3], v20, s13, v[36:37]
	v_mad_i32_i24 v37, v25, s13, v37
	v_lshlrev_b32_e32 v38, 1, v21
	v_mov_b32_e32 v39, v177
	v_lshl_add_u64 v[36:37], v[36:37], 0, v[38:39]
	v_mad_i32_i24 v9, v25, s13, v9
	v_lshl_add_u64 v[52:53], v[36:37], 0, v[176:177]
	s_movk_i32 s2, 0x1000
	v_lshl_add_u64 v[8:9], v[8:9], 0, v[176:177]
	v_lshlrev_b32_e32 v10, 1, v31
	v_mov_b32_e32 v11, v177
	v_add_co_u32_e32 v36, vcc, s2, v52
	v_lshl_add_u64 v[8:9], v[8:9], 0, v[10:11]
	s_nop 0
	v_addc_co_u32_e32 v37, vcc, 0, v53, vcc
	s_movk_i32 s2, 0x2000
	global_load_dwordx4 v[12:15], v[8:9], off offset:2048
	s_nop 0
	global_load_dwordx4 v[8:11], v[8:9], off offset:2064
	v_mov_b32_e32 v20, 0
	global_load_ushort v51, v[36:37], off offset:2560
	v_add_co_u32_e32 v36, vcc, s2, v52
	s_movk_i32 s2, 0x4000
	s_nop 0
	v_addc_co_u32_e32 v37, vcc, 0, v53, vcc
	global_load_ushort v50, v[36:37], off offset:3584
	v_add_co_u32_e32 v36, vcc, s2, v52
	s_movk_i32 s2, 0x5000
	s_nop 0
	v_addc_co_u32_e32 v37, vcc, 0, v53, vcc
	global_load_ushort v40, v[52:53], off offset:1536
	global_load_ushort v49, v[36:37], off offset:512
	v_add_co_u32_e32 v36, vcc, s2, v52
	s_movk_i32 s2, 0x6000
	s_nop 0
	v_addc_co_u32_e32 v37, vcc, 0, v53, vcc
	global_load_ushort v48, v[36:37], off offset:1536
	v_add_co_u32_e32 v36, vcc, s2, v52
	s_movk_i32 s2, 0x7000
	s_nop 0
	v_addc_co_u32_e32 v37, vcc, 0, v53, vcc
	global_load_ushort v47, v[36:37], off offset:2560
	v_add_co_u32_e32 v36, vcc, s2, v52
	s_mov_b32 s2, 0x9000
	s_nop 0
	v_addc_co_u32_e32 v37, vcc, 0, v53, vcc
	global_load_ushort v46, v[36:37], off offset:3584
	v_add_co_u32_e32 v36, vcc, s2, v52
	s_mov_b32 s2, 0xa000
	s_nop 0
	v_addc_co_u32_e32 v37, vcc, 0, v53, vcc
	global_load_ushort v45, v[36:37], off offset:512
	v_add_co_u32_e32 v36, vcc, s2, v52
	s_mov_b32 s2, 0xb000
	s_nop 0
	v_addc_co_u32_e32 v37, vcc, 0, v53, vcc
	global_load_ushort v44, v[36:37], off offset:1536
	v_add_co_u32_e32 v36, vcc, s2, v52
	s_mov_b32 s2, 0xc000
	s_nop 0
	v_addc_co_u32_e32 v37, vcc, 0, v53, vcc
	global_load_ushort v43, v[36:37], off offset:2560
	v_add_co_u32_e32 v36, vcc, s2, v52
	s_mov_b32 s2, 0xe000
	s_nop 0
	v_addc_co_u32_e32 v37, vcc, 0, v53, vcc
	global_load_ushort v42, v[36:37], off offset:3584
	v_add_co_u32_e32 v36, vcc, s2, v52
	s_mov_b32 s2, 0xf000
	s_nop 0
	v_addc_co_u32_e32 v37, vcc, 0, v53, vcc
	global_load_ushort v41, v[36:37], off offset:512
	v_add_co_u32_e32 v36, vcc, s2, v52
	s_mov_b32 s2, 0x10000
	s_nop 0
	v_addc_co_u32_e32 v37, vcc, 0, v53, vcc
	global_load_ushort v39, v[36:37], off offset:1536
	v_add_co_u32_e32 v36, vcc, s2, v52
	s_nop 1
	v_addc_co_u32_e32 v37, vcc, 0, v53, vcc
	global_load_ushort v38, v[36:37], off offset:2560
	v_add_co_u32_e32 v36, vcc, 0x11000, v52
	s_nop 1
	v_addc_co_u32_e32 v37, vcc, 0, v53, vcc
	v_add_co_u32_e32 v52, vcc, 0x13000, v52
	global_load_ushort v37, v[36:37], off offset:3584
	s_nop 0
	v_addc_co_u32_e32 v53, vcc, 0, v53, vcc
	global_load_ushort v35, v[52:53], off offset:512
	s_andn2_b64 vcc, exec, s[30:31]
	v_mov_b32_e32 v36, 0
	v_or_b32_e32 v62, v21, v34
	v_lshlrev_b32_e32 v62, 2, v62
	global_load_dword v63, v62, s[52:53]
	global_load_dword v64, v62, s[52:53] offset:1024
	s_waitcnt vmcnt(0)
	s_cbranch_vccnz .LBB0_234
	v_mov_b32_e32 v36, v63
	v_mov_b32_e32 v34, v64
	s_mov_b32 s2, 0xf149f2ca
	v_max3_f32 v52, v36, s2, v34
	v_sub_f32_e32 v36, v36, v52
	v_sub_f32_e32 v34, v34, v52
	v_mul_f32_e32 v36, 0x3fb8aa3b, v36
	v_mul_f32_e32 v34, 0x3fb8aa3b, v34
	v_exp_f32_e32 v36, v36
	v_exp_f32_e32 v34, v34
	v_mov_b32_e32 v52, v177
	v_add_f32_e32 v53, 0, v36
	v_pk_add_f32 v[52:53], v[34:35], v[52:53] op_sel_hi:[0,1]
	v_div_scale_f32 v34, s[2:3], v53, v53, v52
	v_rcp_f32_e32 v36, v34
	v_div_scale_f32 v54, vcc, v52, v53, v52
	v_fma_f32 v55, -v34, v36, 1.0
	v_fmac_f32_e32 v36, v55, v36
	v_mul_f32_e32 v55, v54, v36
	v_fma_f32 v56, -v34, v55, v54
	v_fmac_f32_e32 v55, v56, v36
	v_fma_f32 v34, -v34, v55, v54
	v_div_fmas_f32 v34, v34, v36, v55
	v_div_fixup_f32 v36, v34, v53, v52
.LBB0_234:
	v_lshlrev_b32_e32 v40, 16, v40
	s_mov_b32 s3, 0xbfb8aa3b
	v_mul_f32_e64 v53, |v40|, s3
	v_lshlrev_b32_e32 v51, 16, v51
	v_exp_f32_e32 v53, v53
	v_mul_f32_e64 v55, |v51|, s3
	v_exp_f32_e32 v55, v55
	v_max_f32_e32 v52, v40, v40
	v_add_f32_e32 v53, 1.0, v53
	v_log_f32_e32 v53, v53
	v_add_f32_e32 v55, 1.0, v55
	v_log_f32_e32 v55, v55
	v_min_f32_e32 v52, 0, v52
	v_max_f32_e32 v54, v51, v51
	v_fmac_f32_e32 v52, 0xbf317218, v53
	v_max_f32_e64 v53, -v40, -v40
	v_min_f32_e32 v54, 0, v54
	v_min_f32_e32 v53, 0x42700000, v53
	v_fmac_f32_e32 v54, 0xbf317218, v55
	v_max_f32_e64 v55, -v51, -v51
	v_mul_f32_e32 v53, 0x3fb8aa3b, v53
	v_min_f32_e32 v55, 0x42700000, v55
	v_exp_f32_e32 v53, v53
	v_mul_f32_e32 v40, 0x3fb8aa3b, v40
	v_mul_f32_e32 v55, 0x3fb8aa3b, v55
	v_exp_f32_e32 v40, v40
	v_exp_f32_e32 v55, v55
	v_mul_f32_e32 v51, 0x3fb8aa3b, v51
	v_exp_f32_e32 v51, v51
	v_fma_f32 v53, v53, v36, 1.0
	v_log_f32_e32 v53, v53
	v_add_f32_e32 v40, 1.0, v40
	v_fma_f32 v55, v55, v36, 1.0
	v_rcp_f32_e32 v40, v40
	v_log_f32_e32 v55, v55
	v_add_f32_e32 v51, 1.0, v51
	v_rcp_f32_e32 v51, v51
	v_lshrrev_b32_e32 v28, 8, v28
	v_sub_f32_e32 v34, 1.0, v36
	v_fmac_f32_e32 v52, 0x3f317218, v53
	s_movk_i32 s2, 0x410
	v_mul_i32_i24_e32 v28, 0xd800, v28
	v_mul_f32_e32 v53, v40, v34
	v_add_f32_e32 v52, 0, v52
	v_mad_u32_u24 v40, v29, s2, v21
	v_fmac_f32_e32 v54, 0x3f317218, v55
	v_lshl_add_u32 v40, v40, 2, v28
	v_mov_b32_e32 v128, v40
	v_add_f32_e32 v54, v54, v52
	v_mul_f32_e32 v51, v51, v34
	v_mov_b32_e32 v129, v52
	v_mov_b32_e32 v130, v54
	v_add_u32_e32 v52, 0x4400, v40
	v_lshlrev_b32_e32 v50, 16, v50
	v_mov_b32_e32 v131, v53
	v_mov_b32_e32 v132, v51
	v_mul_f32_e64 v53, |v50|, s3
	v_exp_f32_e32 v53, v53
	v_max_f32_e32 v51, v50, v50
	v_min_f32_e32 v51, 0, v51
	v_lshlrev_b32_e32 v49, 16, v49
	v_add_f32_e32 v53, 1.0, v53
	v_log_f32_e32 v53, v53
	v_lshlrev_b32_e32 v48, 16, v48
	v_lshlrev_b32_e32 v47, 16, v47
	v_lshlrev_b32_e32 v46, 16, v46
	v_fmac_f32_e32 v51, 0xbf317218, v53
	v_max_f32_e64 v53, -v50, -v50
	v_min_f32_e32 v53, 0x42700000, v53
	v_mul_f32_e32 v53, 0x3fb8aa3b, v53
	v_exp_f32_e32 v53, v53
	v_mul_f32_e32 v50, 0x3fb8aa3b, v50
	v_exp_f32_e32 v50, v50
	v_lshlrev_b32_e32 v45, 16, v45
	v_fma_f32 v53, v53, v36, 1.0
	v_log_f32_e32 v53, v53
	v_add_f32_e32 v50, 1.0, v50
	v_rcp_f32_e32 v50, v50
	v_lshlrev_b32_e32 v44, 16, v44
	v_fmac_f32_e32 v51, 0x3f317218, v53
	v_add_f32_e32 v51, v51, v54
	v_mul_f32_e64 v54, |v49|, s3
	v_exp_f32_e32 v54, v54
	v_max_f32_e32 v53, v49, v49
	v_min_f32_e32 v53, 0, v53
	v_mul_f32_e32 v50, v50, v34
	v_add_f32_e32 v54, 1.0, v54
	v_log_f32_e32 v54, v54
	v_lshlrev_b32_e32 v43, 16, v43
	v_lshlrev_b32_e32 v42, 16, v42
	v_lshlrev_b32_e32 v41, 16, v41
	v_fmac_f32_e32 v53, 0xbf317218, v54
	v_max_f32_e64 v54, -v49, -v49
	v_min_f32_e32 v54, 0x42700000, v54
	v_mul_f32_e32 v54, 0x3fb8aa3b, v54
	v_exp_f32_e32 v54, v54
	v_mul_f32_e32 v49, 0x3fb8aa3b, v49
	v_exp_f32_e32 v49, v49
	v_lshlrev_b32_e32 v39, 16, v39
	v_fma_f32 v54, v54, v36, 1.0
	v_log_f32_e32 v54, v54
	v_add_f32_e32 v49, 1.0, v49
	v_rcp_f32_e32 v49, v49
	v_lshlrev_b32_e32 v38, 16, v38
	v_fmac_f32_e32 v53, 0x3f317218, v54
	v_add_f32_e32 v53, v53, v51
	v_mul_f32_e32 v49, v49, v34
	v_mov_b32_e32 v133, v51
	v_mov_b32_e32 v134, v53
	v_mov_b32_e32 v135, v50
	v_mov_b32_e32 v136, v49
	v_mul_f32_e64 v50, |v48|, s3
	v_exp_f32_e32 v50, v50
	v_max_f32_e32 v49, v48, v48
	v_min_f32_e32 v49, 0, v49
	v_mul_f32_e64 v51, |v47|, s3
	v_add_f32_e32 v50, 1.0, v50
	v_log_f32_e32 v50, v50
	v_exp_f32_e32 v51, v51
	v_lshlrev_b32_e32 v37, 16, v37
	v_lshlrev_b32_e32 v35, 16, v35
	v_fmac_f32_e32 v49, 0xbf317218, v50
	v_max_f32_e64 v50, -v48, -v48
	v_min_f32_e32 v50, 0x42700000, v50
	v_mul_f32_e32 v50, 0x3fb8aa3b, v50
	v_exp_f32_e32 v50, v50
	v_add_f32_e32 v51, 1.0, v51
	v_log_f32_e32 v51, v51
	v_mul_f32_e32 v48, 0x3fb8aa3b, v48
	v_fma_f32 v50, v50, v36, 1.0
	v_log_f32_e32 v50, v50
	v_exp_f32_e32 v48, v48
	v_and_b32_e32 v33, 0xff, v33
	v_mul_u32_u24_e32 v31, 0x48, v31
	v_fmac_f32_e32 v49, 0x3f317218, v50
	v_max_f32_e32 v50, v47, v47
	v_min_f32_e32 v50, 0, v50
	v_fmac_f32_e32 v50, 0xbf317218, v51
	v_max_f32_e64 v51, -v47, -v47
	v_min_f32_e32 v51, 0x42700000, v51
	v_mul_f32_e32 v51, 0x3fb8aa3b, v51
	v_exp_f32_e32 v51, v51
	v_mul_f32_e32 v47, 0x3fb8aa3b, v47
	v_exp_f32_e32 v47, v47
	v_add_f32_e32 v48, 1.0, v48
	v_fma_f32 v51, v51, v36, 1.0
	v_log_f32_e32 v51, v51
	v_add_f32_e32 v47, 1.0, v47
	v_rcp_f32_e32 v48, v48
	v_rcp_f32_e32 v47, v47
	v_add_f32_e32 v49, v49, v53
	v_fmac_f32_e32 v50, 0x3f317218, v51
	v_add_f32_e32 v50, v50, v49
	v_add_u32_e32 v51, 0x400, v40
	v_mul_f32_e32 v48, v48, v34
	v_mul_f32_e32 v47, v47, v34
	v_mov_b32_e32 v137, v49
	v_mov_b32_e32 v138, v50
	v_add_u32_e32 v49, 0x4800, v40
	v_mov_b32_e32 v139, v48
	v_mov_b32_e32 v140, v47
	v_mul_f32_e64 v48, |v46|, s3
	v_exp_f32_e32 v48, v48
	v_max_f32_e32 v47, v46, v46
	v_min_f32_e32 v47, 0, v47
	v_lshlrev_b32_e32 v31, 1, v31
	v_add_f32_e32 v48, 1.0, v48
	v_log_f32_e32 v48, v48
	v_lshlrev_b32_e32 v30, 1, v30
	v_cmp_lt_u32_e32 vcc, 63, v33
	v_fmac_f32_e32 v47, 0xbf317218, v48
	v_max_f32_e64 v48, -v46, -v46
	v_min_f32_e32 v48, 0x42700000, v48
	v_mul_f32_e32 v48, 0x3fb8aa3b, v48
	v_exp_f32_e32 v48, v48
	v_mul_f32_e32 v46, 0x3fb8aa3b, v46
	v_exp_f32_e32 v46, v46
	v_fma_f32 v48, v48, v36, 1.0
	v_log_f32_e32 v48, v48
	v_add_f32_e32 v46, 1.0, v46
	v_rcp_f32_e32 v46, v46
	v_fmac_f32_e32 v47, 0x3f317218, v48
	v_add_f32_e32 v47, v47, v50
	v_mul_f32_e64 v50, |v45|, s3
	v_exp_f32_e32 v50, v50
	v_max_f32_e32 v48, v45, v45
	v_min_f32_e32 v48, 0, v48
	v_mul_f32_e32 v46, v46, v34
	v_add_f32_e32 v50, 1.0, v50
	v_log_f32_e32 v50, v50
	s_nop 0
	v_fmac_f32_e32 v48, 0xbf317218, v50
	v_max_f32_e64 v50, -v45, -v45
	v_min_f32_e32 v50, 0x42700000, v50
	v_mul_f32_e32 v50, 0x3fb8aa3b, v50
	v_exp_f32_e32 v50, v50
	v_mul_f32_e32 v45, 0x3fb8aa3b, v45
	v_exp_f32_e32 v45, v45
	v_fma_f32 v50, v50, v36, 1.0
	v_log_f32_e32 v50, v50
	v_add_f32_e32 v45, 1.0, v45
	v_rcp_f32_e32 v45, v45
	v_fmac_f32_e32 v48, 0x3f317218, v50
	v_add_f32_e32 v48, v48, v47
	v_mul_f32_e32 v45, v45, v34
	v_mov_b32_e32 v141, v47
	v_mov_b32_e32 v142, v48
	v_mov_b32_e32 v143, v46
	v_mov_b32_e32 v144, v45
	v_mul_f32_e64 v46, |v44|, s3
	v_exp_f32_e32 v46, v46
	v_max_f32_e32 v45, v44, v44
	v_min_f32_e32 v45, 0, v45
	v_mul_f32_e64 v47, |v43|, s3
	v_add_f32_e32 v46, 1.0, v46
	v_log_f32_e32 v46, v46
	v_exp_f32_e32 v47, v47
	v_fmac_f32_e32 v45, 0xbf317218, v46
	v_max_f32_e64 v46, -v44, -v44
	v_min_f32_e32 v46, 0x42700000, v46
	v_mul_f32_e32 v46, 0x3fb8aa3b, v46
	v_exp_f32_e32 v46, v46
	v_add_f32_e32 v47, 1.0, v47
	v_log_f32_e32 v47, v47
	v_mul_f32_e32 v44, 0x3fb8aa3b, v44
	v_fma_f32 v46, v46, v36, 1.0
	v_log_f32_e32 v46, v46
	v_exp_f32_e32 v44, v44
	v_fmac_f32_e32 v45, 0x3f317218, v46
	v_max_f32_e32 v46, v43, v43
	v_min_f32_e32 v46, 0, v46
	v_fmac_f32_e32 v46, 0xbf317218, v47
	v_max_f32_e64 v47, -v43, -v43
	v_min_f32_e32 v47, 0x42700000, v47
	v_mul_f32_e32 v47, 0x3fb8aa3b, v47
	v_exp_f32_e32 v47, v47
	v_mul_f32_e32 v43, 0x3fb8aa3b, v43
	v_exp_f32_e32 v43, v43
	v_add_f32_e32 v44, 1.0, v44
	v_fma_f32 v47, v47, v36, 1.0
	v_log_f32_e32 v47, v47
	v_add_f32_e32 v43, 1.0, v43
	v_rcp_f32_e32 v44, v44
	v_rcp_f32_e32 v43, v43
	v_add_f32_e32 v45, v45, v48
	v_fmac_f32_e32 v46, 0x3f317218, v47
	v_add_f32_e32 v46, v46, v45
	v_add_u32_e32 v47, 0x800, v40
	v_mul_f32_e32 v44, v44, v34
	v_mul_f32_e32 v43, v43, v34
	v_mov_b32_e32 v145, v45
	v_mov_b32_e32 v146, v46
	v_add_u32_e32 v45, 0x4c00, v40
	v_mov_b32_e32 v147, v44
	v_mov_b32_e32 v148, v43
	v_mul_f32_e64 v44, |v42|, s3
	v_exp_f32_e32 v44, v44
	v_max_f32_e32 v43, v42, v42
	v_min_f32_e32 v43, 0, v43
	v_add_f32_e32 v44, 1.0, v44
	v_log_f32_e32 v44, v44
	s_nop 0
	v_fmac_f32_e32 v43, 0xbf317218, v44
	v_max_f32_e64 v44, -v42, -v42
	v_min_f32_e32 v44, 0x42700000, v44
	v_mul_f32_e32 v44, 0x3fb8aa3b, v44
	v_exp_f32_e32 v44, v44
	v_mul_f32_e32 v42, 0x3fb8aa3b, v42
	v_exp_f32_e32 v42, v42
	v_fma_f32 v44, v44, v36, 1.0
	v_log_f32_e32 v44, v44
	v_add_f32_e32 v42, 1.0, v42
	v_rcp_f32_e32 v42, v42
	v_fmac_f32_e32 v43, 0x3f317218, v44
	v_add_f32_e32 v43, v43, v46
	v_mul_f32_e64 v46, |v41|, s3
	v_exp_f32_e32 v46, v46
	v_max_f32_e32 v44, v41, v41
	v_min_f32_e32 v44, 0, v44
	v_mul_f32_e32 v42, v42, v34
	v_add_f32_e32 v46, 1.0, v46
	v_log_f32_e32 v46, v46
	s_nop 0
	v_fmac_f32_e32 v44, 0xbf317218, v46
	v_max_f32_e64 v46, -v41, -v41
	v_min_f32_e32 v46, 0x42700000, v46
	v_mul_f32_e32 v46, 0x3fb8aa3b, v46
	v_exp_f32_e32 v46, v46
	v_mul_f32_e32 v41, 0x3fb8aa3b, v41
	v_exp_f32_e32 v41, v41
	v_fma_f32 v46, v46, v36, 1.0
	v_log_f32_e32 v46, v46
	v_add_f32_e32 v41, 1.0, v41
	v_rcp_f32_e32 v41, v41
	v_fmac_f32_e32 v44, 0x3f317218, v46
	v_add_f32_e32 v44, v44, v43
	v_mul_f32_e32 v41, v41, v34
	v_mov_b32_e32 v149, v43
	v_mov_b32_e32 v150, v44
	v_mov_b32_e32 v151, v42
	v_mov_b32_e32 v152, v41
	v_mul_f32_e64 v42, |v39|, s3
	v_exp_f32_e32 v42, v42
	v_max_f32_e32 v41, v39, v39
	v_min_f32_e32 v41, 0, v41
	v_mul_f32_e64 v43, |v38|, s3
	v_add_f32_e32 v42, 1.0, v42
	v_log_f32_e32 v42, v42
	v_exp_f32_e32 v43, v43
	v_fmac_f32_e32 v41, 0xbf317218, v42
	v_max_f32_e64 v42, -v39, -v39
	v_min_f32_e32 v42, 0x42700000, v42
	v_mul_f32_e32 v42, 0x3fb8aa3b, v42
	v_exp_f32_e32 v42, v42
	v_add_f32_e32 v43, 1.0, v43
	v_log_f32_e32 v43, v43
	v_mul_f32_e32 v39, 0x3fb8aa3b, v39
	v_fma_f32 v42, v42, v36, 1.0
	v_log_f32_e32 v42, v42
	v_exp_f32_e32 v39, v39
	v_fmac_f32_e32 v41, 0x3f317218, v42
	v_max_f32_e32 v42, v38, v38
	v_min_f32_e32 v42, 0, v42
	v_fmac_f32_e32 v42, 0xbf317218, v43
	v_max_f32_e64 v43, -v38, -v38
	v_min_f32_e32 v43, 0x42700000, v43
	v_mul_f32_e32 v43, 0x3fb8aa3b, v43
	v_mul_f32_e32 v38, 0x3fb8aa3b, v38
	v_exp_f32_e32 v43, v43
	v_exp_f32_e32 v38, v38
	v_add_f32_e32 v39, 1.0, v39
	v_rcp_f32_e32 v39, v39
	v_fma_f32 v43, v43, v36, 1.0
	v_add_f32_e32 v38, 1.0, v38
	v_log_f32_e32 v43, v43
	v_rcp_f32_e32 v38, v38
	v_mul_f32_e32 v39, v39, v34
	v_add_f32_e32 v41, v41, v44
	v_fmac_f32_e32 v42, 0x3f317218, v43
	v_mul_f32_e32 v38, v38, v34
	v_add_u32_e32 v43, 0xc00, v40
	v_add_u32_e32 v40, 0x5000, v40
	v_mov_b32_e32 v153, v39
	v_mov_b32_e32 v154, v38
	v_mul_f32_e64 v39, |v37|, s3
	v_exp_f32_e32 v39, v39
	v_max_f32_e32 v38, v37, v37
	v_min_f32_e32 v38, 0, v38
	v_add_f32_e32 v42, v42, v41
	v_add_f32_e32 v39, 1.0, v39
	v_log_f32_e32 v39, v39
	v_mov_b32_e32 v155, v41
	v_mov_b32_e32 v156, v42
	v_mul_f32_e64 v41, |v35|, s3
	v_exp_f32_e32 v41, v41
	v_fmac_f32_e32 v38, 0xbf317218, v39
	v_max_f32_e64 v39, -v37, -v37
	v_min_f32_e32 v39, 0x42700000, v39
	v_mul_f32_e32 v39, 0x3fb8aa3b, v39
	v_exp_f32_e32 v39, v39
	v_add_f32_e32 v41, 1.0, v41
	v_log_f32_e32 v41, v41
	v_mul_f32_e32 v37, 0x3fb8aa3b, v37
	v_fma_f32 v39, v39, v36, 1.0
	v_log_f32_e32 v39, v39
	v_exp_f32_e32 v37, v37
	v_fmac_f32_e32 v38, 0x3f317218, v39
	v_max_f32_e32 v39, v35, v35
	v_min_f32_e32 v39, 0, v39
	v_fmac_f32_e32 v39, 0xbf317218, v41
	v_max_f32_e64 v41, -v35, -v35
	v_min_f32_e32 v41, 0x42700000, v41
	v_mul_f32_e32 v41, 0x3fb8aa3b, v41
	v_exp_f32_e32 v41, v41
	v_mul_f32_e32 v35, 0x3fb8aa3b, v35
	v_exp_f32_e32 v35, v35
	v_add_f32_e32 v37, 1.0, v37
	v_fma_f32 v36, v41, v36, 1.0
	v_log_f32_e32 v36, v36
	v_add_f32_e32 v35, 1.0, v35
	v_rcp_f32_e32 v37, v37
	v_rcp_f32_e32 v35, v35
	v_add_f32_e32 v38, v38, v42
	v_fmac_f32_e32 v39, 0x3f317218, v36
	v_mul_f32_e32 v37, v37, v34
	v_mul_f32_e32 v34, v35, v34
	v_add_f32_e32 v35, v39, v38
	v_mov_b32_e32 v157, v38
	v_mov_b32_e32 v158, v35
	v_mov_b32_e32 v159, v37
	v_mov_b32_e32 v160, v34
	v_lshl_add_u32 v34, v33, 2, v28
	s_barrier
	v_add_u32_e32 v161, 0x400, v128
	v_add_u32_e32 v162, 0x800, v128
	v_add_u32_e32 v163, 0xc00, v128
	v_add_u32_e32 v164, 0x4400, v128
	v_add_u32_e32 v165, 0x4800, v128
	v_add_u32_e32 v166, 0x4c00, v128
	v_add_u32_e32 v167, 0x5000, v128
	ds_write2_b32 v128, v129, v130 offset1:65
	ds_write2_b32 v164, v131, v132 offset1:65
	ds_write2_b32 v128, v133, v134 offset0:130 offset1:195
	ds_write2_b32 v164, v135, v136 offset0:130 offset1:195
	ds_write2_b32 v161, v137, v138 offset0:4 offset1:69
	ds_write2_b32 v165, v139, v140 offset0:4 offset1:69
	ds_write2_b32 v161, v141, v142 offset0:134 offset1:199
	ds_write2_b32 v165, v143, v144 offset0:134 offset1:199
	ds_write2_b32 v162, v145, v146 offset0:8 offset1:73
	ds_write2_b32 v166, v147, v148 offset0:8 offset1:73
	ds_write2_b32 v162, v149, v150 offset0:138 offset1:203
	ds_write2_b32 v166, v151, v152 offset0:138 offset1:203
	ds_write2_b32 v167, v153, v154 offset0:12 offset1:77
	ds_write2_b32 v163, v155, v156 offset0:12 offset1:77
	ds_write2_b32 v163, v157, v158 offset0:142 offset1:207
	ds_write2_b32 v167, v159, v160 offset0:142 offset1:207
	ds_write_b32 v34, v35 offset:53248
	v_add3_u32 v34, v28, v31, v30
	v_add3_u32 v30, v28, v30, v31
	ds_write_b16 v34, v12 offset:34816
	ds_write_b16_d16_hi v30, v12 offset:34960
	ds_write_b16 v34, v13 offset:35104
	ds_write_b16_d16_hi v30, v13 offset:35248
	ds_write_b16 v34, v14 offset:35392
	ds_write_b16_d16_hi v30, v14 offset:35536
	ds_write_b16 v34, v15 offset:35680
	ds_write_b16_d16_hi v30, v15 offset:35824
	ds_write_b16 v34, v8 offset:35968
	ds_write_b16_d16_hi v30, v8 offset:36112
	ds_write_b16 v34, v9 offset:36256
	ds_write_b16_d16_hi v30, v9 offset:36400
	ds_write_b16 v34, v10 offset:36544
	ds_write_b16_d16_hi v30, v10 offset:36688
	ds_write_b16 v34, v11 offset:36832
	ds_write_b16_d16_hi v30, v11 offset:36976
	s_waitcnt lgkmcnt(0)
	s_barrier
	s_and_saveexec_b64 s[2:3], vcc
	s_cbranch_execz .LBB0_238
	v_lshlrev_b32_e32 v8, 2, v21
	s_mov_b32 s4, 0xd000
	v_add3_u32 v8, v28, v8, s4
	v_mov_b32_e32 v20, 0
	s_mov_b64 s[4:5], 0
